# first XCD-local arriver at barriers 1-5 and 8 starts the L2 write-back early (asynchronously)
# baseline (speedup 1.0000x reference)
; __device__ __forceinline__ unsigned xb_ld(unsigned* p)              { return __hip_atomic_load(p, __ATOMIC_RELAXED, __HIP_MEMORY_SCOPE_AGENT); }
; __device__ __forceinline__ unsigned xb_add(unsigned* p, unsigned v) { return __hip_atomic_fetch_add(p, v, __ATOMIC_RELAXED, __HIP_MEMORY_SCOPE_AGENT); }
; #define XB_SPIN(cond, bar) do { unsigned _sp = 0; while (cond) { __builtin_amdgcn_s_sleep(1); \
;     if ((++_sp & 255u) == 0u) { if (xb_ld(&(bar)[XB_TMO])) break; if (_sp > XB_SPIN_CAP) { atomicAdd(&(bar)[XB_TMO], 1u); break; } } } } while (0)
; __device__ __forceinline__ void xcd_barrier(const XcdBarrier& b) {
;     ...
;         const unsigned old = xb_add(&bar[XB_XSUB(b.x)], 1u);
;         const unsigned gen = old / nloc;
;         if (old + 1u == (gen + 1u) * nloc) {
;             __builtin_amdgcn_fence(__ATOMIC_RELEASE, "agent");
;             asm volatile("s_waitcnt vmcnt(0)" ::: "memory");
;             const unsigned og = xb_add(&bar[XB_TOP], 1u);
;             const unsigned tg = og / nx;
;             if (og + 1u == (tg + 1u) * nx) xb_add(&bar[XB_TOPGEN], 1u);
;             else XB_SPIN(xb_ld(&bar[XB_TOPGEN]) == tg, bar);
;             __builtin_amdgcn_fence(__ATOMIC_ACQUIRE, "agent");
;             xb_add(&bar[XB_XGEN(b.x)], 1u);
;             asm volatile("s_waitcnt vmcnt(0)" ::: "memory");
;         } else {
;             XB_SPIN(xb_ld(&bar[XB_XGEN(b.x)]) == gen, bar);
;             __builtin_amdgcn_fence(__ATOMIC_ACQUIRE, "agent");
.LBB0_66:
	s_or_b64 exec, exec, s[8:9]
	v_cvt_f32_u32_e32 v4, v2
	s_waitcnt vmcnt(0)
	v_readfirstlane_b32 s3, v3
	v_sub_u32_e32 v3, 0, v2
	v_rcp_iflag_f32_e32 v4, v4
	v_add_u32_e32 v5, s3, v1
	v_mul_f32_e32 v4, 0x4f7ffffe, v4
	v_cvt_u32_f32_e32 v4, v4
	v_mul_lo_u32 v1, v3, v4
	v_mul_hi_u32 v1, v4, v1
	v_add_u32_e32 v1, v4, v1
	v_mul_hi_u32 v1, v5, v1
	v_mul_lo_u32 v3, v1, v2
	v_sub_u32_e32 v3, v5, v3
	v_add_u32_e32 v4, 1, v1
	v_cmp_ge_u32_e32 vcc, v3, v2
	s_nop 1
	v_cndmask_b32_e32 v1, v1, v4, vcc
	v_sub_u32_e32 v4, v3, v2
	v_cndmask_b32_e32 v3, v3, v4, vcc
	v_add_u32_e32 v4, 1, v1
	v_cmp_ge_u32_e32 vcc, v3, v2
	v_add_u32_e32 v3, 1, v5
	s_nop 0
	v_cndmask_b32_e32 v1, v1, v4, vcc
	v_mul_lo_u32 v4, v2, v1
	v_add_u32_e32 v2, v4, v2
	v_cmp_ne_u32_e32 vcc, v3, v2
	s_and_saveexec_b64 s[6:7], vcc
	s_xor_b64 s[6:7], exec, s[6:7]
	s_cbranch_execz .LBB0_80
	s_waitcnt lgkmcnt(0)
	buffer_inv sc1
	v_cmp_eq_u32_e32 vcc, v5, v4
	s_cbranch_vccz .Lewb_1
	buffer_wbl2 sc1
.Lewb_1:
	v_mov_b32_e32 v0, 0x2000
	global_load_dword v0, v0, s[4:5] offset:1024 sc1
	s_add_u32 s14, s4, 0x2400
	s_addc_u32 s15, s5, 0
	s_waitcnt vmcnt(0)
	v_cmp_eq_u32_e32 vcc, v0, v1
	s_and_saveexec_b64 s[8:9], vcc
	s_cbranch_execz .LBB0_79
	s_add_u32 s12, s68, 0x80200
	s_addc_u32 s13, s69, 0
	s_mov_b32 s3, 1
	s_mov_b64 s[16:17], 0
	v_mov_b32_e32 v0, 0
	s_branch .LBB0_70

; __device__ __forceinline__ unsigned xb_ld(unsigned* p)              { return __hip_atomic_load(p, __ATOMIC_RELAXED, __HIP_MEMORY_SCOPE_AGENT); }
; #define XB_SPIN(cond, bar) do { unsigned _sp = 0; while (cond) { __builtin_amdgcn_s_sleep(1); \
;     if ((++_sp & 255u) == 0u) { if (xb_ld(&(bar)[XB_TMO])) break; if (_sp > XB_SPIN_CAP) { atomicAdd(&(bar)[XB_TMO], 1u); break; } } } } while (0)
; __device__ __forceinline__ void xcd_barrier(const XcdBarrier& b) {
;     ...
;         } else {
;             XB_SPIN(xb_ld(&bar[XB_XGEN(b.x)]) == gen, bar);
;             __builtin_amdgcn_fence(__ATOMIC_ACQUIRE, "agent");
;             asm volatile("s_waitcnt vmcnt(0)" ::: "memory");
.Lewb_3:
	v_mov_b32_e32 v0, 0x2000
	global_load_dword v0, v0, s[4:5] offset:1024 sc1
	s_add_u32 s12, s4, 0x2400
	s_addc_u32 s13, s5, 0
	s_waitcnt vmcnt(0)
	v_cmp_eq_u32_e32 vcc, v0, v1
	s_and_saveexec_b64 s[8:9], vcc
	s_cbranch_execz .LBB0_649
	s_add_u32 s10, s68, 0x80200
	s_addc_u32 s11, s69, 0
	s_mov_b32 s3, 1
	s_mov_b64 s[14:15], 0
	v_mov_b32_e32 v0, 0
	s_branch .LBB0_640

; __device__ __forceinline__ unsigned xb_ld(unsigned* p)              { return __hip_atomic_load(p, __ATOMIC_RELAXED, __HIP_MEMORY_SCOPE_AGENT); }
; __device__ __forceinline__ unsigned xb_add(unsigned* p, unsigned v) { return __hip_atomic_fetch_add(p, v, __ATOMIC_RELAXED, __HIP_MEMORY_SCOPE_AGENT); }
; #define XB_SPIN(cond, bar) do { unsigned _sp = 0; while (cond) { __builtin_amdgcn_s_sleep(1); \
;     if ((++_sp & 255u) == 0u) { if (xb_ld(&(bar)[XB_TMO])) break; if (_sp > XB_SPIN_CAP) { atomicAdd(&(bar)[XB_TMO], 1u); break; } } } } while (0)
; __device__ __forceinline__ void xcd_barrier(const XcdBarrier& b) {
;     ...
;         const unsigned old = xb_add(&bar[XB_XSUB(b.x)], 1u);
;         const unsigned gen = old / nloc;
;         if (old + 1u == (gen + 1u) * nloc) {
;             __builtin_amdgcn_fence(__ATOMIC_RELEASE, "agent");
;             asm volatile("s_waitcnt vmcnt(0)" ::: "memory");
;             const unsigned og = xb_add(&bar[XB_TOP], 1u);
;             const unsigned tg = og / nx;
;             if (og + 1u == (tg + 1u) * nx) xb_add(&bar[XB_TOPGEN], 1u);
;             else XB_SPIN(xb_ld(&bar[XB_TOPGEN]) == tg, bar);
;             __builtin_amdgcn_fence(__ATOMIC_ACQUIRE, "agent");
;             xb_add(&bar[XB_XGEN(b.x)], 1u);
;             asm volatile("s_waitcnt vmcnt(0)" ::: "memory");
;         } else {
;             XB_SPIN(xb_ld(&bar[XB_XGEN(b.x)]) == gen, bar);
;             __builtin_amdgcn_fence(__ATOMIC_ACQUIRE, "agent");
;             asm volatile("s_waitcnt vmcnt(0)" ::: "memory");
.LBB0_1120:
	s_or_b64 exec, exec, s[8:9]
	v_cvt_f32_u32_e32 v4, v2
	s_waitcnt vmcnt(0)
	v_readfirstlane_b32 s4, v3
	v_sub_u32_e32 v3, 0, v2
	v_rcp_iflag_f32_e32 v4, v4
	v_add_u32_e32 v5, s4, v1
	v_mul_f32_e32 v4, 0x4f7ffffe, v4
	v_cvt_u32_f32_e32 v4, v4
	v_mul_lo_u32 v1, v3, v4
	v_mul_hi_u32 v1, v4, v1
	v_add_u32_e32 v1, v4, v1
	v_mul_hi_u32 v1, v5, v1
	v_mul_lo_u32 v3, v1, v2
	v_sub_u32_e32 v3, v5, v3
	v_add_u32_e32 v4, 1, v1
	v_cmp_ge_u32_e32 vcc, v3, v2
	s_nop 1
	v_cndmask_b32_e32 v1, v1, v4, vcc
	v_sub_u32_e32 v4, v3, v2
	v_cndmask_b32_e32 v3, v3, v4, vcc
	v_add_u32_e32 v4, 1, v1
	v_cmp_ge_u32_e32 vcc, v3, v2
	v_add_u32_e32 v3, 1, v5
	s_nop 0
	v_cndmask_b32_e32 v1, v1, v4, vcc
	v_mul_lo_u32 v4, v2, v1
	v_add_u32_e32 v2, v4, v2
	v_cmp_ne_u32_e32 vcc, v3, v2
	s_and_saveexec_b64 s[4:5], vcc
	s_xor_b64 s[4:5], exec, s[4:5]
	s_cbranch_execz .LBB0_1134
	s_waitcnt lgkmcnt(0)
	buffer_inv sc1
	v_cmp_eq_u32_e32 vcc, v5, v4
	s_cbranch_vccz .Lewb_8
	buffer_wbl2 sc1
.Lewb_8:
	v_mov_b32_e32 v0, 0x2000
	global_load_dword v0, v0, s[2:3] offset:1024 sc1
	s_add_u32 s12, s2, 0x2400
	s_addc_u32 s13, s3, 0
	s_waitcnt vmcnt(0)
	v_cmp_eq_u32_e32 vcc, v0, v1
	s_and_saveexec_b64 s[8:9], vcc
	s_cbranch_execz .LBB0_1133
	s_add_u32 s10, s68, 0x80200
	s_addc_u32 s11, s69, 0
	s_mov_b32 s24, 1
	s_mov_b64 s[14:15], 0
	v_mov_b32_e32 v0, 0
	s_branch .LBB0_1124
